# t30 + neighbourhood-bias LDS reads in the masked attention step use one base register with immediate offsets (16 fewer VALU per step); dead pad keeps downstream layout
# speedup vs baseline: 1.0055x; 1.0055x over previous
; #define LAS __attribute__((address_space(3)))
; #define MFMA32(a, b, c) __builtin_amdgcn_mfma_f32_32x32x16_bf16((a), (b), (c), 0, 0, 0)
;     __device__ __forceinline__ float operator()(float s, int kc, int h, int qr) const { const int d = dk + kc + 4 * h - qr; return (d >= -128 && d <= 128) ? s * (ATT_SCALE * LOG2E) : NEG_BIG; }
; template <class ScoreFn>
; __device__ __forceinline__ void attn_step(AttnState& st, const bf16x8 (&qf)[4], LAS unsigned char* kb, LAS unsigned char* vb, int lane, const ScoreFn& sf) {
;     ...
;     LAS unsigned char* kp = kb + r * KVP; const int kx = (h ^ (r & 7)) << 4;
; #pragma unroll
;     for (int ds = 0; ds < 4; ++ds) {
;         const bf16x8 k0 = *(const LAS bf16x8*)(kp + (kx ^ (ds << 5))), k1 = *(const LAS bf16x8*)(kp + 32 * KVP + (kx ^ (ds << 5)));
;         s0 = MFMA32(k0, qf[ds], s0); s1 = MFMA32(k1, qf[ds], s1);
;     }
;     float mt = NEG_BIG;
;     __builtin_amdgcn_sched_barrier(0);
; #pragma unroll
;     for (int i = 0; i < 16; ++i) { s0[i] = sf(s0[i], (i & 3) + 8 * (i >> 2), h, r); mt = fmaxf(mt, s0[i]); if ((i & 7) == 7) __builtin_amdgcn_sched_barrier(0); }
; #pragma unroll
;     for (int i = 0; i < 16; ++i) { s1[i] = sf(s1[i], 32 + (i & 3) + 8 * (i >> 2), h, r); mt = fmaxf(mt, s1[i]); if ((i & 7) == 7) __builtin_amdgcn_sched_barrier(0); }
;     mt = fmaxf(mt, __shfl_xor(mt, 32));
;     __device__ __forceinline__ float operator()(float s, int kc, int, int) const {
;         const float b = *(const LAS float*)(tbs + 4 * kc);
;         return (kc >= lo4 && kc < lo4 + 16) ? fmaf(s, ATT_SCALE * LOG2E, b) : NEG_BIG;
;     }
.LBB0_620:
	s_andn2_b64 vcc, exec, s[74:75]
	s_cbranch_vccnz .LBB0_624
	s_add_i32 s1, s76, s82
	v_cmp_ge_u32_e32 vcc, s1, v94
	v_cmp_lt_u32_e64 s[74:75], s1, v95
	s_and_b64 s[2:3], vcc, s[74:75]
	s_andn2_b64 vcc, exec, s[2:3]
	s_cbranch_vccnz .LBB0_623
	s_mov_b32 s1, 0
	s_nop 0
	v_add_u32_e32 v38, s1, v139
	ds_read_b128 v[34:37], v38
	ds_read_b128 v[50:53], v38 offset:4096
	v_add_u32_e32 v58, s1, v138
	ds_read_b128 v[54:57], v58
	ds_read_b128 v[84:87], v58 offset:4096
	v_add_u32_e32 v59, s1, v137
	v_add_u32_e32 v58, s1, v136
	v_add_u32_e32 v66, 0x184a0, v109
	s_waitcnt lgkmcnt(0)
	v_mfma_f32_32x32x16_bf16 v[34:49], v[34:37], v[68:71], 0
	ds_read_b128 v[88:91], v59 offset:4096
	ds_read_b128 v[136:139], v58 offset:4096
	v_mfma_f32_32x32x16_bf16 v[34:49], v[54:57], v[72:75], v[34:49]
	ds_read_b128 v[54:57], v59
	s_waitcnt lgkmcnt(0)
	v_mfma_f32_32x32x16_bf16 v[34:49], v[54:57], v[76:79], v[34:49]
	ds_read_b128 v[54:57], v58
	s_waitcnt lgkmcnt(0)
	v_mfma_f32_32x32x16_bf16 v[34:49], v[54:57], v[80:83], v[34:49]
	ds_read2_b32 v[140:141], v66 offset1:1
	ds_read2_b32 v[142:143], v66 offset0:2 offset1:3
	ds_read2_b32 v[144:145], v66 offset0:8 offset1:9
	ds_read2_b32 v[146:147], v66 offset0:10 offset1:11
	ds_read2_b32 v[148:149], v66 offset0:16 offset1:17
	ds_read2_b32 v[150:151], v66 offset0:18 offset1:19
	ds_read2_b32 v[152:153], v66 offset0:24 offset1:25
	ds_read2_b32 v[154:155], v66 offset0:26 offset1:27
	v_mfma_f32_32x32x16_bf16 v[50:65], v[50:53], v[68:71], 0
	v_mfma_f32_32x32x16_bf16 v[50:65], v[84:87], v[72:75], v[50:65]
	v_mfma_f32_32x32x16_bf16 v[50:65], v[88:91], v[76:79], v[50:65]
	ds_read2_b32 v[84:85], v66 offset0:32 offset1:33
	ds_read2_b32 v[86:87], v66 offset0:34 offset1:35
	ds_read2_b32 v[88:89], v66 offset0:40 offset1:41
	ds_read2_b32 v[90:91], v66 offset0:42 offset1:43
	v_mfma_f32_32x32x16_bf16 v[50:65], v[136:139], v[80:83], v[50:65]
	ds_read2_b32 v[136:137], v66 offset0:48 offset1:49
	ds_read2_b32 v[138:139], v66 offset0:50 offset1:51
	ds_read2_b32 v[156:157], v66 offset0:56 offset1:57
	ds_read2_b32 v[158:159], v66 offset0:58 offset1:59
	s_waitcnt lgkmcnt(0)
	v_fmamk_f32 v34, v34, 0x3e38aa3b, v140
	v_fmac_f32_e32 v141, 0x3e38aa3b, v35
	v_cndmask_b32_e64 v34, v250, v34, s[6:7]
	v_cndmask_b32_e64 v35, v250, v141, s[8:9]
	s_mov_b32 s1, 0xf149f2ca
	v_fmamk_f32 v36, v36, 0x3e38aa3b, v142
	v_fmac_f32_e32 v143, 0x3e38aa3b, v37
	v_max3_f32 v66, v34, s1, v35
	v_cndmask_b32_e64 v140, v250, v36, s[10:11]
	v_cndmask_b32_e64 v141, v250, v143, s[12:13]
	v_fmamk_f32 v37, v38, 0x3e38aa3b, v144
	v_fmac_f32_e32 v145, 0x3e38aa3b, v39
	v_max3_f32 v36, v66, v140, v141
	v_cndmask_b32_e64 v142, v250, v37, s[14:15]
	v_cndmask_b32_e64 v143, v250, v145, s[16:17]
	v_fmamk_f32 v37, v40, 0x3e38aa3b, v146
	v_fmac_f32_e32 v147, 0x3e38aa3b, v41
	v_max3_f32 v36, v36, v142, v143
	v_cndmask_b32_e64 v144, v250, v37, s[18:19]
	v_cndmask_b32_e64 v145, v250, v147, s[20:21]
	v_fmamk_f32 v37, v42, 0x3e38aa3b, v148
	v_fmac_f32_e32 v149, 0x3e38aa3b, v43
	v_max3_f32 v36, v36, v144, v145
	v_cndmask_b32_e64 v146, v250, v37, s[22:23]
	v_cndmask_b32_e64 v43, v250, v149, s[24:25]
	v_fmamk_f32 v37, v44, 0x3e38aa3b, v150
	v_fmac_f32_e32 v151, 0x3e38aa3b, v45
	v_max3_f32 v36, v36, v146, v43
	v_cndmask_b32_e64 v147, v250, v37, s[26:27]
	v_cndmask_b32_e64 v148, v250, v151, s[28:29]
	v_fmamk_f32 v37, v46, 0x3e38aa3b, v152
	v_fmac_f32_e32 v153, 0x3e38aa3b, v47
	v_max3_f32 v36, v36, v147, v148
	v_cndmask_b32_e64 v46, v250, v37, s[30:31]
	v_cndmask_b32_e64 v47, v250, v153, s[34:35]
	v_fmamk_f32 v37, v48, 0x3e38aa3b, v154
	v_fmac_f32_e32 v155, 0x3e38aa3b, v49
	v_max3_f32 v36, v36, v46, v47
	v_cndmask_b32_e64 v149, v250, v37, s[36:37]
	v_cndmask_b32_e64 v150, v250, v155, s[38:39]
	v_fmamk_f32 v37, v50, 0x3e38aa3b, v84
	v_fmac_f32_e32 v85, 0x3e38aa3b, v51
	v_max3_f32 v36, v36, v149, v150
	v_cndmask_b32_e64 v37, v250, v37, s[40:41]
	v_cndmask_b32_e64 v38, v250, v85, s[42:43]
	v_fmamk_f32 v39, v52, 0x3e38aa3b, v86
	v_fmac_f32_e32 v87, 0x3e38aa3b, v53
	v_max3_f32 v36, v36, v37, v38
	v_cndmask_b32_e64 v39, v250, v39, s[44:45]
	v_cndmask_b32_e64 v40, v250, v87, s[46:47]
	v_fmamk_f32 v41, v54, 0x3e38aa3b, v88
	v_fmac_f32_e32 v89, 0x3e38aa3b, v55
	v_max3_f32 v36, v36, v39, v40
	v_cndmask_b32_e64 v44, v250, v41, s[48:49]
	v_cndmask_b32_e64 v45, v250, v89, s[50:51]
	v_fmamk_f32 v41, v56, 0x3e38aa3b, v90
	v_fmac_f32_e32 v91, 0x3e38aa3b, v57
	v_max3_f32 v36, v36, v44, v45
	v_cndmask_b32_e64 v50, v250, v41, s[52:53]
	v_cndmask_b32_e64 v51, v250, v91, s[54:55]
	v_fmamk_f32 v41, v58, 0x3e38aa3b, v136
	v_fmac_f32_e32 v137, 0x3e38aa3b, v59
	v_max3_f32 v36, v36, v50, v51
	v_cndmask_b32_e64 v56, v250, v41, s[56:57]
	v_cndmask_b32_e64 v57, v250, v137, s[58:59]
	v_fmamk_f32 v41, v60, 0x3e38aa3b, v138
	v_fmac_f32_e32 v139, 0x3e38aa3b, v61
	v_max3_f32 v36, v36, v56, v57
	v_cndmask_b32_e64 v60, v250, v41, s[60:61]
	v_cndmask_b32_e64 v61, v250, v139, s[62:63]
	v_fmamk_f32 v41, v62, 0x3e38aa3b, v156
	v_fmac_f32_e32 v157, 0x3e38aa3b, v63
	v_max3_f32 v36, v36, v60, v61
	v_cndmask_b32_e64 v84, v250, v41, s[64:65]
	v_cndmask_b32_e64 v85, v250, v157, s[66:67]
	v_fmamk_f32 v41, v64, 0x3e38aa3b, v158
	v_fmac_f32_e32 v159, 0x3e38aa3b, v65
	v_cmp_lt_i32_e32 vcc, v242, v241
	v_max3_f32 v36, v36, v84, v85
	v_cndmask_b32_e64 v86, v250, v41, s[68:69]
	v_cndmask_b32_e64 v87, v250, v159, s[70:71]
	v_cndmask_b32_e32 v41, v240, v242, vcc
	v_max3_f32 v36, v36, v86, v87
	v_lshlrev_b32_e32 v41, 2, v41
	ds_bpermute_b32 v41, v41, v36
	s_waitcnt lgkmcnt(0)
; #define LAS __attribute__((address_space(3)))
; #define MFMA32(a, b, c) __builtin_amdgcn_mfma_f32_32x32x16_bf16((a), (b), (c), 0, 0, 0)
; __device__ __forceinline__ unsigned cvtpk(float lo, float hi) { return pg8::cvt_pk_bf16(lo, hi); }
; template <class ScoreFn>
; __device__ __forceinline__ void attn_step(AttnState& st, const bf16x8 (&qf)[4], LAS unsigned char* kb, LAS unsigned char* vb, int lane, const ScoreFn& sf) {
;     ...
;     mt = fmaxf(mt, __shfl_xor(mt, 32));
;     const float mn = fmaxf(st.m, mt), alpha = __builtin_amdgcn_exp2f(st.m - mn);
;     float ps = 0.f;
; #pragma unroll
;     for (int i = 0; i < 16; ++i) { s0[i] = __builtin_amdgcn_exp2f(s0[i] - mn); s1[i] = __builtin_amdgcn_exp2f(s1[i] - mn); ps += s0[i] + s1[i]; }
;     st.l = st.l * alpha + ps; st.m = mn;
; #pragma unroll
;     for (int i = 0; i < 16; ++i) { st.o0[i] *= alpha; st.o1[i] *= alpha; }
;     __builtin_amdgcn_sched_barrier(0);
;     v4u pw[4];
;     pw[0].x = cvtpk(s0[0], s0[1]); pw[0].y = cvtpk(s0[2], s0[3]); pw[0].z = cvtpk(s0[4], s0[5]); pw[0].w = cvtpk(s0[6], s0[7]);
;     pw[1].x = cvtpk(s0[8], s0[9]); pw[1].y = cvtpk(s0[10], s0[11]); pw[1].z = cvtpk(s0[12], s0[13]); pw[1].w = cvtpk(s0[14], s0[15]);
;     pw[2].x = cvtpk(s1[0], s1[1]); pw[2].y = cvtpk(s1[2], s1[3]); pw[2].z = cvtpk(s1[4], s1[5]); pw[2].w = cvtpk(s1[6], s1[7]);
;     pw[3].x = cvtpk(s1[8], s1[9]); pw[3].y = cvtpk(s1[10], s1[11]); pw[3].z = cvtpk(s1[12], s1[13]); pw[3].w = cvtpk(s1[14], s1[15]);
;     const int i16 = lane & 15, q = i16 >> 2, p = i16 & 3, dhalf = (lane >> 4) & 1;
;     LAS unsigned char* vrow = vb + (4 * h + q) * KVP + (p & 1) * 8;
;     LAS unsigned char* vp0 = vrow + (((2 * dhalf + (p >> 1)) ^ (4 * h + q)) << 4); LAS unsigned char* vp1 = vrow + (((4 + 2 * dhalf + (p >> 1)) ^ (4 * h + q)) << 4);
; #pragma unroll
;     for (int ks = 0; ks < 4; ++ks) {
;         const s16x4 l0 = tr_read(vp0 + (16 * ks) * KVP), h0 = tr_read(vp0 + (16 * ks + 8) * KVP);
;         const s16x4 l1 = tr_read(vp1 + (16 * ks) * KVP), h1 = tr_read(vp1 + (16 * ks + 8) * KVP);
;         const bf16x8 v0 = (bf16x8){l0[0], l0[1], l0[2], l0[3], h0[0], h0[1], h0[2], h0[3]};
;         const bf16x8 v1 = (bf16x8){l1[0], l1[1], l1[2], l1[3], h1[0], h1[1], h1[2], h1[3]};
;         const bf16x8 pf = __builtin_bit_cast(bf16x8, pw[ks]);
;         st.o0 = MFMA32(v0, pf, st.o0); st.o1 = MFMA32(v1, pf, st.o1);
;     }
	v_max3_f32 v42, v131, v36, v41
	v_sub_f32_e32 v34, v34, v42
	v_exp_f32_e32 v88, v34
	v_sub_f32_e32 v34, v37, v42
	v_exp_f32_e32 v89, v34
	v_sub_f32_e32 v34, v35, v42
	v_exp_f32_e32 v66, v34
	v_sub_f32_e32 v34, v38, v42
	v_exp_f32_e32 v34, v34
	v_add_f32_e32 v35, v89, v88
	v_sub_f32_e32 v38, v40, v42
	v_exp_f32_e32 v40, v38
	v_pk_add_f32 v[36:37], v[34:35], v[66:67]
	v_sub_f32_e32 v35, v140, v42
	v_pk_add_f32 v[36:37], v[36:37], v[36:37] op_sel_hi:[0,1]
	v_sub_f32_e32 v36, v39, v42
	v_exp_f32_e32 v35, v35
	v_exp_f32_e32 v90, v36
	v_sub_f32_e32 v36, v141, v42
	v_exp_f32_e32 v36, v36
	v_sub_f32_e32 v43, v43, v42
	v_add_f32_e32 v41, v90, v35
	v_pk_add_f32 v[38:39], v[40:41], v[36:37]
	s_nop 0
	v_pk_add_f32 v[38:39], v[38:39], v[38:39] op_sel_hi:[0,1]
	v_sub_f32_e32 v37, v142, v42
	v_sub_f32_e32 v38, v44, v42
	v_exp_f32_e32 v37, v37
	v_exp_f32_e32 v41, v38
	v_sub_f32_e32 v38, v143, v42
	v_sub_f32_e32 v44, v45, v42
	v_exp_f32_e32 v38, v38
	v_exp_f32_e32 v52, v44
	v_add_f32_e32 v53, v41, v37
	v_pk_add_f32 v[44:45], v[52:53], v[38:39]
	s_nop 0
	v_pk_add_f32 v[48:49], v[44:45], v[44:45] op_sel_hi:[0,1]
	v_sub_f32_e32 v44, v50, v42
	v_sub_f32_e32 v39, v144, v42
	v_exp_f32_e32 v53, v44
	v_sub_f32_e32 v44, v145, v42
	v_exp_f32_e32 v39, v39
	v_exp_f32_e32 v48, v44
	v_sub_f32_e32 v44, v51, v42
	v_exp_f32_e32 v54, v44
	v_add_f32_e32 v55, v53, v39
	v_pk_add_f32 v[44:45], v[54:55], v[48:49]
	s_nop 0
	v_pk_add_f32 v[50:51], v[44:45], v[44:45] op_sel_hi:[0,1]
	v_sub_f32_e32 v44, v146, v42
	v_exp_f32_e32 v49, v44
	v_sub_f32_e32 v44, v56, v42
	v_exp_f32_e32 v55, v44
	v_exp_f32_e32 v50, v43
	v_sub_f32_e32 v43, v57, v42
	v_exp_f32_e32 v56, v43
	v_add_f32_e32 v57, v55, v49
	v_sub_f32_e32 v43, v147, v42
	v_exp_f32_e32 v43, v43
	v_pk_add_f32 v[44:45], v[56:57], v[50:51]
	s_nop 0
	v_pk_add_f32 v[58:59], v[44:45], v[44:45] op_sel_hi:[0,1]
	v_sub_f32_e32 v44, v60, v42
	v_exp_f32_e32 v57, v44
	v_sub_f32_e32 v44, v148, v42
	v_exp_f32_e32 v58, v44
	v_sub_f32_e32 v44, v61, v42
	v_exp_f32_e32 v60, v44
	v_add_f32_e32 v61, v57, v43
	v_pk_add_f32 v[44:45], v[60:61], v[58:59]
	s_nop 0
	v_pk_add_f32 v[62:63], v[44:45], v[44:45] op_sel_hi:[0,1]
	v_sub_f32_e32 v44, v46, v42
	v_exp_f32_e32 v51, v44
	v_sub_f32_e32 v44, v84, v42
	v_exp_f32_e32 v59, v44
	v_sub_f32_e32 v44, v47, v42
	v_exp_f32_e32 v62, v44
	v_sub_f32_e32 v44, v85, v42
	v_exp_f32_e32 v64, v44
	v_add_f32_e32 v65, v59, v51
	v_pk_add_f32 v[44:45], v[64:65], v[62:63]
	s_nop 0
	v_pk_add_f32 v[84:85], v[44:45], v[44:45] op_sel_hi:[0,1]
	v_sub_f32_e32 v44, v149, v42
	v_exp_f32_e32 v61, v44
	v_sub_f32_e32 v44, v86, v42
	v_exp_f32_e32 v63, v44
	v_sub_f32_e32 v44, v150, v42
	v_exp_f32_e32 v84, v44
	v_sub_f32_e32 v44, v87, v42
	v_exp_f32_e32 v86, v44
	v_sub_f32_e32 v44, v131, v42
	v_exp_f32_e32 v44, v44
	v_add_f32_e32 v87, v63, v61
	v_pk_add_f32 v[46:47], v[86:87], v[84:85]
	v_pk_mul_f32 v[32:33], v[32:33], v[44:45] op_sel_hi:[1,0]
	v_add_f32_e32 v65, v46, v47
	v_pk_mul_f32 v[30:31], v[30:31], v[44:45] op_sel_hi:[1,0]
	v_pk_mul_f32 v[28:29], v[28:29], v[44:45] op_sel_hi:[1,0]
	v_pk_mul_f32 v[26:27], v[26:27], v[44:45] op_sel_hi:[1,0]
	v_pk_mul_f32 v[24:25], v[24:25], v[44:45] op_sel_hi:[1,0]
	v_pk_mul_f32 v[22:23], v[22:23], v[44:45] op_sel_hi:[1,0]
	v_pk_mul_f32 v[20:21], v[20:21], v[44:45] op_sel_hi:[1,0]
	v_pk_mul_f32 v[18:19], v[18:19], v[44:45] op_sel_hi:[1,0]
	v_pk_mul_f32 v[16:17], v[16:17], v[44:45] op_sel_hi:[1,0]
	v_pk_mul_f32 v[14:15], v[14:15], v[44:45] op_sel_hi:[1,0]
	v_pk_mul_f32 v[12:13], v[12:13], v[44:45] op_sel_hi:[1,0]
	v_pk_mul_f32 v[10:11], v[10:11], v[44:45] op_sel_hi:[1,0]
	v_pk_mul_f32 v[8:9], v[8:9], v[44:45] op_sel_hi:[1,0]
	v_pk_mul_f32 v[6:7], v[6:7], v[44:45] op_sel_hi:[1,0]
	v_pk_mul_f32 v[4:5], v[4:5], v[44:45] op_sel_hi:[1,0]
	v_pk_mul_f32 v[2:3], v[2:3], v[44:45] op_sel_hi:[1,0]
	v_fmac_f32_e32 v65, v130, v44
	v_cvt_pk_bf16_f32 v47, v39, v48
	v_cvt_pk_bf16_f32 v48, v49, v50
	v_cvt_pk_bf16_f32 v49, v43, v58
	v_cvt_pk_bf16_f32 v46, v37, v38
	v_cvt_pk_bf16_f32 v38, v89, v34
	v_cvt_pk_bf16_f32 v39, v90, v40
	v_cvt_pk_bf16_f32 v40, v41, v52
	v_cvt_pk_bf16_f32 v41, v53, v54
	v_cvt_pk_bf16_f32 v34, v55, v56
	ds_read_b64_tr_b16 v[52:53], v134
	v_cvt_pk_bf16_f32 v45, v35, v36
	v_cvt_pk_bf16_f32 v35, v57, v60
	ds_read_b64_tr_b16 v[54:55], v133
	ds_read_b64_tr_b16 v[56:57], v135
	v_cvt_pk_bf16_f32 v36, v59, v64
	ds_read_b64_tr_b16 v[58:59], v132
	v_cvt_pk_bf16_f32 v44, v88, v66
	v_cvt_pk_bf16_f32 v50, v51, v62
	s_waitcnt lgkmcnt(2)
	v_mfma_f32_32x32x16_bf16 v[18:33], v[52:55], v[44:47], v[18:33]
	v_cvt_pk_bf16_f32 v51, v61, v84
	v_cvt_pk_bf16_f32 v37, v63, v86
	v_mov_b32_e32 v130, v65
	v_mov_b32_e32 v131, v42
	s_waitcnt lgkmcnt(0)
	v_mfma_f32_32x32x16_bf16 v[2:17], v[56:59], v[44:47], v[2:17]
	ds_read_b64_tr_b16 v[44:45], v129
	ds_read_b64_tr_b16 v[46:47], v128
	ds_read_b64_tr_b16 v[52:53], v127
	ds_read_b64_tr_b16 v[54:55], v126
	s_waitcnt lgkmcnt(2)
	v_mfma_f32_32x32x16_bf16 v[18:33], v[44:47], v[48:51], v[18:33]
	ds_read_b64_tr_b16 v[44:45], v125
	ds_read_b64_tr_b16 v[46:47], v124
	s_waitcnt lgkmcnt(2)
	v_mfma_f32_32x32x16_bf16 v[2:17], v[52:55], v[48:51], v[2:17]
	ds_read_b64_tr_b16 v[48:49], v123
	ds_read_b64_tr_b16 v[50:51], v122
	s_waitcnt lgkmcnt(2)
	v_mfma_f32_32x32x16_bf16 v[18:33], v[44:47], v[38:41], v[18:33]
	ds_read_b64_tr_b16 v[44:45], v119
	ds_read_b64_tr_b16 v[46:47], v118
	s_waitcnt lgkmcnt(2)
	v_mfma_f32_32x32x16_bf16 v[2:17], v[48:51], v[38:41], v[2:17]
	ds_read_b64_tr_b16 v[38:39], v121
	ds_read_b64_tr_b16 v[40:41], v120
	s_waitcnt lgkmcnt(0)
	v_mfma_f32_32x32x16_bf16 v[18:33], v[38:41], v[34:37], v[18:33]
	v_mfma_f32_32x32x16_bf16 v[2:17], v[44:47], v[34:37], v[2:17]

; #define LAS __attribute__((address_space(3)))
; #define WG_BAR() do { asm volatile("s_waitcnt lgkmcnt(0)" ::: "memory"); __builtin_amdgcn_s_barrier(); asm volatile("" ::: "memory"); } while (0)
; #define ATT_DMA(t) do { const int t_ = (t) < NS ? (t) : NS - 1; const size_t ro_ = (size_t)TILE_ROW(t_) * ZC; LAS unsigned char* d_ = dk0 + ((t) % ATT_NB) * KV_BUF; \
;         __builtin_amdgcn_global_load_lds((const unsigned*)(gk + ro_), (LAS unsigned*)d_, 16, 0, 0); __builtin_amdgcn_global_load_lds((const unsigned*)(gv + ro_), (LAS unsigned*)(d_ + KV_TILE), 16, 0, 0); } while (0)
; template <bool ISB>
; __device__ __forceinline__ void attn_wg_item(Frame& F, int l, int idx) {
;     ...
;     for (int s = 0; s < NS; ++s) {
;         ATT_DMA(s + ATT_D);
;         asm volatile("s_waitcnt vmcnt(8)" ::: "memory");
;         WG_BAR();
;         LAS unsigned char* cur = ring + (s % ATT_NB) * KV_BUF;
;         if (s >= nloc) { ScorePlain sf; attn_step(st, qf, cur, cur + KV_TILE, lane, sf); }
;         else if (!ISB) { int dkv = krow_base + 64 * s - qrow0; asm volatile("" : "+v"(dkv)); ScoreWin sf{dkv}; attn_step(st, qf, cur, cur + KV_TILE, lane, sf); }
;         else { const int gr = r0 + (w >> 1); int kr0 = gr - 4; kr0 = kr0 < 0 ? 0 : (kr0 > 120 ? 120 : kr0); const int kr = kmin + s;
;             if (kr >= kr0 && kr < kr0 + 8) { const int cq = 32 * (w & 1) + (lane & 31), hh = lane >> 5; int cs = cq - 8; cs = cs < 0 ? 0 : (cs > 48 ? 48 : cs);
;                 ScoreNb sf{(LAS unsigned char*)(tab + 64) + ((kr - gr + 7) * 31 + 15 - cq + 4 * hh) * 4, cs - 4 * hh}; attn_step(st, qf, cur, cur + KV_TILE, lane, sf); } }
;     }
.Lb623_exit:
	v_mov_b32_e32 v140, v131
	v_mov_b32_e32 v141, v130
	s_nop 8
	v_mov_b32_e32 v34, v18
	v_mov_b32_e32 v35, v19
	v_mov_b32_e32 v36, v20
	v_mov_b32_e32 v37, v21
	v_mov_b32_e32 v38, v22
	v_mov_b32_e32 v39, v23
	v_mov_b32_e32 v40, v24
	v_mov_b32_e32 v41, v25
	v_mov_b32_e32 v42, v26
	v_mov_b32_e32 v43, v27
	v_mov_b32_e32 v44, v28
	v_mov_b32_e32 v45, v29
	v_mov_b32_e32 v46, v30
	v_mov_b32_e32 v47, v31
	v_mov_b32_e32 v48, v32
	v_mov_b32_e32 v49, v33
	v_mov_b32_e32 v50, v2
	v_mov_b32_e32 v51, v3
	v_mov_b32_e32 v52, v4
	v_mov_b32_e32 v53, v5
	v_mov_b32_e32 v54, v6
	v_mov_b32_e32 v55, v7
	v_mov_b32_e32 v56, v8
	v_mov_b32_e32 v57, v9
	v_mov_b32_e32 v58, v10
	v_mov_b32_e32 v59, v11
	v_mov_b32_e32 v60, v12
	v_mov_b32_e32 v61, v13
	v_mov_b32_e32 v62, v14
	v_mov_b32_e32 v63, v15
	v_mov_b32_e32 v64, v16
	v_mov_b32_e32 v65, v17
	s_branch .LBB0_626
	s_nop 0
	s_nop 0
	s_nop 0
	s_nop 0
	s_nop 0
	s_nop 0
	s_nop 0
	s_nop 0
	s_nop 0
	s_nop 0
	s_nop 0
	s_nop 0
	s_nop 0
	s_nop 0
	s_nop 0
	s_nop 0
	s_nop 0
	s_nop 0
	s_nop 0
	s_nop 0
	s_nop 0
	s_nop 0
	s_nop 0
	s_nop 0
	s_nop 0
	s_nop 0
	s_nop 0
	s_nop 0
	s_nop 0
	s_nop 0
	s_nop 0
	s_nop 0
	s_nop 0
	s_nop 0
	s_nop 0
	s_nop 0
	s_nop 0
